# P1: next tile's first A/B K-tile lines touched at the start of the epilogue (L2 warm-up for the next prologue)
# baseline (speedup 1.0000x reference)
; DEVINL float sigm(float x) { return 1.f / (1.f + __expf(-x)); }
; template <int EPI, bool GATHER>
; DEVINL void gemm_tile(const Params& p, const u16* __restrict__ A, int lda, const int* __restrict__ rowidx,
;                       const u16* __restrict__ Bt, int ldb, int K, int brow, int bcol, int orow, int ocol) {
;     ...
;   const int row0 = orow + wr * 64 + fq * 4;
;   const int col0 = ocol + wc * 32 + fr;
;   const bool odd = (fr & 1) != 0;
;   const int colp = col0 - (odd ? 1 : 0);
; #pragma unroll
;   for (int ai = 0; ai < 2; ++ai)
; #pragma unroll
;     for (int m = 0; m < 4; ++m) {
;       const int rA = row0 + ai * HALF + m * 16 + (odd ? 2 : 0);
;       float gate[2] = {0.f, 0.f};
;       if (EPI == EPI_MOE2) { gate[0] = ((const float*)(ws + O_SELG))[rA]; gate[1] = ((const float*)(ws + O_SELG))[rA + 1]; }
; #pragma unroll
;       for (int bj = 0; bj < (EPI == EPI_HID ? 1 : 2); ++bj)
; #pragma unroll
;         for (int n = 0; n < 2; ++n) {
;           const int cc = bj * HALF + n * 16;
;           f32x4 v = acc[ai][bj][m][n];
;           if (EPI == EPI_HID) {
; #pragma unroll
;             for (int j = 0; j < 4; ++j) { const float a1 = acc[ai][0][m][n][j], a3 = acc[ai][1][m][n][j]; v[j] = a1 * sigm(a1) * a3; }
;           }
;           float lo[2], hi[2];
;           xchg_pairs(v, odd, lo, hi);
; #pragma unroll
;           for (int k = 0; k < 2; ++k) {
;             const unsigned row = (unsigned)(rA + k);
;             if (EPI == EPI_HID) {
;               *(unsigned*)(ws + O_HID + (row * 1024u + (unsigned)(colp + cc)) * 2u) = pk2(lo[k], hi[k]);
;             } else if (EPI == EPI_COLS) {
;               *(unsigned*)(ws + O_COLS + (row * (unsigned)NCP + (unsigned)(colp + cc)) * 2u) = pk2(lo[k], hi[k]);
.LBB0_223:
	s_or_b64 exec, exec, s[6:7]
	s_add_u32 s4, s47, 0x100
	s_lshr_b32 s6, s4, 5
	s_and_b32 s7, s4, 31
	s_lshl_b32 s6, s6, 20
	s_lshl_b32 s7, s7, 20
	s_add_u32 s6, s6, 0x2000000
	v_lshrrev_b32_e32 v247, 1, v189
	v_and_b32_e32 v248, 1, v189
	v_lshlrev_b32_e32 v247, 12, v247
	v_lshl_add_u32 v247, v248, 7, v247
	v_add_u32_e32 v248, s6, v247
	v_add_u32_e32 v249, s7, v247
	global_load_dword v246, v248, s[92:93]
	global_load_dword v250, v249, s[92:93]
	v_and_b32_e32 v130, 1, v141
	v_add_u32_e32 v128, s48, v145
	v_lshlrev_b32_e32 v129, 2, v144
	v_lshlrev_b32_e32 v131, 1, v130
	v_or3_b32 v128, v128, v131, v129
	v_or_b32_e32 v129, s78, v143
	v_cmp_eq_u32_e32 vcc, 0, v130
	v_sub_u32_e32 v129, v129, v130
	s_movk_i32 s4, 0x2a00
	v_cndmask_b32_e32 v130, v124, v126, vcc
	v_cndmask_b32_e32 v131, v125, v127, vcc
	v_lshl_add_u32 v129, v142, 5, v129
	v_mov_b32_dpp v130, v130 quad_perm:[1,0,3,2] row_mask:0xf bank_mask:0xf bound_ctrl:1
	v_cndmask_b32_e32 v124, v130, v124, vcc
	v_cndmask_b32_e32 v126, v126, v130, vcc
	v_mov_b32_dpp v131, v131 quad_perm:[1,0,3,2] row_mask:0xf bank_mask:0xf bound_ctrl:1
	v_cvt_pk_bf16_f32 v124, v124, v126
	v_mul_lo_u32 v126, v128, s4
	v_cndmask_b32_e32 v125, v131, v125, vcc
	v_cndmask_b32_e32 v127, v127, v131, vcc
	v_add_lshl_u32 v128, v126, v129, 1
	global_store_dword v128, v124, s[0:1]
	v_cvt_pk_bf16_f32 v124, v125, v127
	v_add_u32_e32 v125, 0x2a00, v126
	v_add_lshl_u32 v127, v125, v129, 1
	global_store_dword v127, v124, s[0:1]
	v_cndmask_b32_e32 v124, v116, v118, vcc
	v_cndmask_b32_e32 v127, v117, v119, vcc
	s_nop 0
	v_mov_b32_dpp v124, v124 quad_perm:[1,0,3,2] row_mask:0xf bank_mask:0xf bound_ctrl:1
	v_mov_b32_dpp v127, v127 quad_perm:[1,0,3,2] row_mask:0xf bank_mask:0xf bound_ctrl:1
	v_cndmask_b32_e32 v116, v124, v116, vcc
	v_cndmask_b32_e32 v118, v118, v124, vcc
	v_add_u32_e32 v124, 16, v129
	v_cndmask_b32_e32 v117, v127, v117, vcc
	v_cndmask_b32_e32 v119, v119, v127, vcc
	v_cvt_pk_bf16_f32 v116, v116, v118
	v_add_lshl_u32 v118, v126, v124, 1
	global_store_dword v118, v116, s[0:1]
	v_cvt_pk_bf16_f32 v116, v117, v119
	v_add_lshl_u32 v117, v125, v124, 1
	global_store_dword v117, v116, s[0:1]
	v_cndmask_b32_e32 v117, v120, v122, vcc
	v_cndmask_b32_e32 v118, v121, v123, vcc
	v_add_u32_e32 v116, 0x80, v129
	v_mov_b32_dpp v117, v117 quad_perm:[1,0,3,2] row_mask:0xf bank_mask:0xf bound_ctrl:1
	v_mov_b32_dpp v118, v118 quad_perm:[1,0,3,2] row_mask:0xf bank_mask:0xf bound_ctrl:1
	v_cndmask_b32_e32 v119, v117, v120, vcc
	v_cndmask_b32_e32 v117, v122, v117, vcc
	v_cndmask_b32_e32 v120, v118, v121, vcc
	v_cndmask_b32_e32 v118, v123, v118, vcc
	v_cvt_pk_bf16_f32 v117, v119, v117
	v_add_lshl_u32 v119, v126, v116, 1
	global_store_dword v119, v117, s[0:1]
	v_cvt_pk_bf16_f32 v117, v120, v118
	v_add_lshl_u32 v118, v125, v116, 1
	global_store_dword v118, v117, s[0:1]
	v_cndmask_b32_e32 v117, v112, v114, vcc
	v_cndmask_b32_e32 v118, v113, v115, vcc
	s_nop 0
	v_mov_b32_dpp v117, v117 quad_perm:[1,0,3,2] row_mask:0xf bank_mask:0xf bound_ctrl:1
	v_mov_b32_dpp v118, v118 quad_perm:[1,0,3,2] row_mask:0xf bank_mask:0xf bound_ctrl:1
	v_cndmask_b32_e32 v112, v117, v112, vcc
	v_cndmask_b32_e32 v114, v114, v117, vcc
	v_add_u32_e32 v117, 0x90, v129
	v_cndmask_b32_e32 v113, v118, v113, vcc
	v_cndmask_b32_e32 v115, v115, v118, vcc
	v_cvt_pk_bf16_f32 v112, v112, v114
	v_add_lshl_u32 v114, v126, v117, 1
	global_store_dword v114, v112, s[0:1]
	v_cvt_pk_bf16_f32 v112, v113, v115
	v_add_lshl_u32 v113, v125, v117, 1
	global_store_dword v113, v112, s[0:1]
	v_cndmask_b32_e32 v112, v108, v110, vcc
	v_cndmask_b32_e32 v113, v109, v111, vcc
	s_nop 0
	v_mov_b32_dpp v112, v112 quad_perm:[1,0,3,2] row_mask:0xf bank_mask:0xf bound_ctrl:1
	v_cndmask_b32_e32 v108, v112, v108, vcc
	v_cndmask_b32_e32 v110, v110, v112, vcc
	v_mov_b32_dpp v113, v113 quad_perm:[1,0,3,2] row_mask:0xf bank_mask:0xf bound_ctrl:1
	v_cvt_pk_bf16_f32 v108, v108, v110
	v_add_u32_e32 v110, 0x2a000, v126
	v_cndmask_b32_e32 v109, v113, v109, vcc
	v_cndmask_b32_e32 v111, v111, v113, vcc
	v_add_lshl_u32 v112, v110, v129, 1
	global_store_dword v112, v108, s[0:1]
	v_cvt_pk_bf16_f32 v108, v109, v111
	v_add_u32_e32 v109, 0x2ca00, v126
	v_add_lshl_u32 v111, v109, v129, 1
	global_store_dword v111, v108, s[0:1]
	v_cndmask_b32_e32 v108, v100, v102, vcc
	v_cndmask_b32_e32 v111, v101, v103, vcc
	s_nop 0
	v_mov_b32_dpp v108, v108 quad_perm:[1,0,3,2] row_mask:0xf bank_mask:0xf bound_ctrl:1
	v_mov_b32_dpp v111, v111 quad_perm:[1,0,3,2] row_mask:0xf bank_mask:0xf bound_ctrl:1
	v_cndmask_b32_e32 v100, v108, v100, vcc
	v_cndmask_b32_e32 v102, v102, v108, vcc
	v_cndmask_b32_e32 v101, v111, v101, vcc
	v_cndmask_b32_e32 v103, v103, v111, vcc
	v_cvt_pk_bf16_f32 v100, v100, v102
	v_add_lshl_u32 v102, v110, v124, 1
	global_store_dword v102, v100, s[0:1]
	v_cvt_pk_bf16_f32 v100, v101, v103
	v_add_lshl_u32 v101, v109, v124, 1
	global_store_dword v101, v100, s[0:1]
	v_cndmask_b32_e32 v100, v104, v106, vcc
	v_cndmask_b32_e32 v101, v105, v107, vcc
	s_nop 0
	v_mov_b32_dpp v100, v100 quad_perm:[1,0,3,2] row_mask:0xf bank_mask:0xf bound_ctrl:1
	v_mov_b32_dpp v101, v101 quad_perm:[1,0,3,2] row_mask:0xf bank_mask:0xf bound_ctrl:1
	v_cndmask_b32_e32 v102, v100, v104, vcc
	v_cndmask_b32_e32 v100, v106, v100, vcc
	v_cndmask_b32_e32 v103, v101, v105, vcc
	v_cndmask_b32_e32 v101, v107, v101, vcc
	v_cvt_pk_bf16_f32 v100, v102, v100
	v_add_lshl_u32 v102, v110, v116, 1
	global_store_dword v102, v100, s[0:1]
	v_cvt_pk_bf16_f32 v100, v103, v101
	v_add_lshl_u32 v101, v109, v116, 1
	global_store_dword v101, v100, s[0:1]
	v_cndmask_b32_e32 v100, v96, v98, vcc
	v_cndmask_b32_e32 v101, v97, v99, vcc
	s_nop 0
; DEVINL float sigm(float x) { return 1.f / (1.f + __expf(-x)); }
; template <int EPI, bool GATHER>
; DEVINL void gemm_tile(const Params& p, const u16* __restrict__ A, int lda, const int* __restrict__ rowidx,
;                       const u16* __restrict__ Bt, int ldb, int K, int brow, int bcol, int orow, int ocol) {
;     ...
; #pragma unroll
;   for (int ai = 0; ai < 2; ++ai)
; #pragma unroll
;     for (int m = 0; m < 4; ++m) {
;       const int rA = row0 + ai * HALF + m * 16 + (odd ? 2 : 0);
;       float gate[2] = {0.f, 0.f};
;       if (EPI == EPI_MOE2) { gate[0] = ((const float*)(ws + O_SELG))[rA]; gate[1] = ((const float*)(ws + O_SELG))[rA + 1]; }
; #pragma unroll
;       for (int bj = 0; bj < (EPI == EPI_HID ? 1 : 2); ++bj)
; #pragma unroll
;         for (int n = 0; n < 2; ++n) {
;           const int cc = bj * HALF + n * 16;
;           f32x4 v = acc[ai][bj][m][n];
;           if (EPI == EPI_HID) {
; #pragma unroll
;             for (int j = 0; j < 4; ++j) { const float a1 = acc[ai][0][m][n][j], a3 = acc[ai][1][m][n][j]; v[j] = a1 * sigm(a1) * a3; }
;           }
;           float lo[2], hi[2];
;           xchg_pairs(v, odd, lo, hi);
; #pragma unroll
;           for (int k = 0; k < 2; ++k) {
;             const unsigned row = (unsigned)(rA + k);
;             if (EPI == EPI_HID) {
;               *(unsigned*)(ws + O_HID + (row * 1024u + (unsigned)(colp + cc)) * 2u) = pk2(lo[k], hi[k]);
;             } else if (EPI == EPI_COLS) {
;               *(unsigned*)(ws + O_COLS + (row * (unsigned)NCP + (unsigned)(colp + cc)) * 2u) = pk2(lo[k], hi[k]);
	v_mov_b32_dpp v100, v100 quad_perm:[1,0,3,2] row_mask:0xf bank_mask:0xf bound_ctrl:1
	v_mov_b32_dpp v101, v101 quad_perm:[1,0,3,2] row_mask:0xf bank_mask:0xf bound_ctrl:1
	v_cndmask_b32_e32 v96, v100, v96, vcc
	v_cndmask_b32_e32 v98, v98, v100, vcc
	v_cndmask_b32_e32 v97, v101, v97, vcc
	v_cndmask_b32_e32 v99, v99, v101, vcc
	v_cvt_pk_bf16_f32 v96, v96, v98
	v_add_lshl_u32 v98, v110, v117, 1
	global_store_dword v98, v96, s[0:1]
	v_cvt_pk_bf16_f32 v96, v97, v99
	v_add_lshl_u32 v97, v109, v117, 1
	global_store_dword v97, v96, s[0:1]
	v_cndmask_b32_e32 v96, v92, v94, vcc
	v_cndmask_b32_e32 v97, v93, v95, vcc
	s_nop 0
	v_mov_b32_dpp v96, v96 quad_perm:[1,0,3,2] row_mask:0xf bank_mask:0xf bound_ctrl:1
	v_cndmask_b32_e32 v92, v96, v92, vcc
	v_cndmask_b32_e32 v94, v94, v96, vcc
	v_mov_b32_dpp v97, v97 quad_perm:[1,0,3,2] row_mask:0xf bank_mask:0xf bound_ctrl:1
	v_cvt_pk_bf16_f32 v92, v92, v94
	v_add_u32_e32 v94, 0x54000, v126
	v_cndmask_b32_e32 v93, v97, v93, vcc
	v_cndmask_b32_e32 v95, v95, v97, vcc
	v_add_lshl_u32 v96, v94, v129, 1
	global_store_dword v96, v92, s[0:1]
	v_cvt_pk_bf16_f32 v92, v93, v95
	v_add_u32_e32 v93, 0x56a00, v126
	v_add_lshl_u32 v95, v93, v129, 1
	global_store_dword v95, v92, s[0:1]
	v_cndmask_b32_e32 v92, v84, v86, vcc
	v_cndmask_b32_e32 v95, v85, v87, vcc
	s_nop 0
	v_mov_b32_dpp v92, v92 quad_perm:[1,0,3,2] row_mask:0xf bank_mask:0xf bound_ctrl:1
	v_mov_b32_dpp v95, v95 quad_perm:[1,0,3,2] row_mask:0xf bank_mask:0xf bound_ctrl:1
	v_cndmask_b32_e32 v84, v92, v84, vcc
	v_cndmask_b32_e32 v86, v86, v92, vcc
	v_cndmask_b32_e32 v85, v95, v85, vcc
	v_cndmask_b32_e32 v87, v87, v95, vcc
	v_cvt_pk_bf16_f32 v84, v84, v86
	v_add_lshl_u32 v86, v94, v124, 1
	global_store_dword v86, v84, s[0:1]
	v_cvt_pk_bf16_f32 v84, v85, v87
	v_add_lshl_u32 v85, v93, v124, 1
	global_store_dword v85, v84, s[0:1]
	v_cndmask_b32_e32 v84, v88, v90, vcc
	v_cndmask_b32_e32 v85, v89, v91, vcc
	s_nop 0
	v_mov_b32_dpp v84, v84 quad_perm:[1,0,3,2] row_mask:0xf bank_mask:0xf bound_ctrl:1
	v_mov_b32_dpp v85, v85 quad_perm:[1,0,3,2] row_mask:0xf bank_mask:0xf bound_ctrl:1
	v_cndmask_b32_e32 v86, v84, v88, vcc
	v_cndmask_b32_e32 v84, v90, v84, vcc
	v_cndmask_b32_e32 v87, v85, v89, vcc
	v_cndmask_b32_e32 v85, v91, v85, vcc
	v_cvt_pk_bf16_f32 v84, v86, v84
	v_add_lshl_u32 v86, v94, v116, 1
	global_store_dword v86, v84, s[0:1]
	v_cvt_pk_bf16_f32 v84, v87, v85
	v_add_lshl_u32 v85, v93, v116, 1
	global_store_dword v85, v84, s[0:1]
	v_cndmask_b32_e32 v84, v80, v82, vcc
	v_cndmask_b32_e32 v85, v81, v83, vcc
	s_nop 0
	v_mov_b32_dpp v84, v84 quad_perm:[1,0,3,2] row_mask:0xf bank_mask:0xf bound_ctrl:1
	v_mov_b32_dpp v85, v85 quad_perm:[1,0,3,2] row_mask:0xf bank_mask:0xf bound_ctrl:1
	v_cndmask_b32_e32 v80, v84, v80, vcc
	v_cndmask_b32_e32 v82, v82, v84, vcc
	v_cndmask_b32_e32 v81, v85, v81, vcc
	v_cndmask_b32_e32 v83, v83, v85, vcc
	v_cvt_pk_bf16_f32 v80, v80, v82
	v_add_lshl_u32 v82, v94, v117, 1
	global_store_dword v82, v80, s[0:1]
	v_cvt_pk_bf16_f32 v80, v81, v83
	v_add_lshl_u32 v81, v93, v117, 1
	global_store_dword v81, v80, s[0:1]
	v_cndmask_b32_e32 v80, v76, v78, vcc
	v_cndmask_b32_e32 v81, v77, v79, vcc
	s_nop 0
	v_mov_b32_dpp v80, v80 quad_perm:[1,0,3,2] row_mask:0xf bank_mask:0xf bound_ctrl:1
	v_cndmask_b32_e32 v76, v80, v76, vcc
	v_cndmask_b32_e32 v78, v78, v80, vcc
	v_mov_b32_dpp v81, v81 quad_perm:[1,0,3,2] row_mask:0xf bank_mask:0xf bound_ctrl:1
	v_cvt_pk_bf16_f32 v76, v76, v78
	v_add_u32_e32 v78, 0x7e000, v126
	v_cndmask_b32_e32 v77, v81, v77, vcc
	v_cndmask_b32_e32 v79, v79, v81, vcc
	v_add_lshl_u32 v80, v78, v129, 1
	global_store_dword v80, v76, s[0:1]
	v_cvt_pk_bf16_f32 v76, v77, v79
	v_add_u32_e32 v77, 0x80a00, v126
	v_add_lshl_u32 v79, v77, v129, 1
	global_store_dword v79, v76, s[0:1]
	v_cndmask_b32_e32 v76, v68, v70, vcc
	v_cndmask_b32_e32 v79, v69, v71, vcc
	s_nop 0
	v_mov_b32_dpp v76, v76 quad_perm:[1,0,3,2] row_mask:0xf bank_mask:0xf bound_ctrl:1
	v_mov_b32_dpp v79, v79 quad_perm:[1,0,3,2] row_mask:0xf bank_mask:0xf bound_ctrl:1
	v_cndmask_b32_e32 v68, v76, v68, vcc
	v_cndmask_b32_e32 v70, v70, v76, vcc
	v_cndmask_b32_e32 v69, v79, v69, vcc
	v_cndmask_b32_e32 v71, v71, v79, vcc
	v_cvt_pk_bf16_f32 v68, v68, v70
	v_add_lshl_u32 v70, v78, v124, 1
	global_store_dword v70, v68, s[0:1]
	v_cvt_pk_bf16_f32 v68, v69, v71
	v_add_lshl_u32 v69, v77, v124, 1
	global_store_dword v69, v68, s[0:1]
	v_cndmask_b32_e32 v68, v72, v74, vcc
	v_cndmask_b32_e32 v69, v73, v75, vcc
	s_nop 0
	v_mov_b32_dpp v68, v68 quad_perm:[1,0,3,2] row_mask:0xf bank_mask:0xf bound_ctrl:1
	v_mov_b32_dpp v69, v69 quad_perm:[1,0,3,2] row_mask:0xf bank_mask:0xf bound_ctrl:1
	v_cndmask_b32_e32 v70, v68, v72, vcc
	v_cndmask_b32_e32 v68, v74, v68, vcc
	v_cndmask_b32_e32 v71, v69, v73, vcc
	v_cndmask_b32_e32 v69, v75, v69, vcc
	v_cvt_pk_bf16_f32 v68, v70, v68
	v_add_lshl_u32 v70, v78, v116, 1
	global_store_dword v70, v68, s[0:1]
	v_cvt_pk_bf16_f32 v68, v71, v69
	v_add_lshl_u32 v69, v77, v116, 1
	global_store_dword v69, v68, s[0:1]
	v_cndmask_b32_e32 v68, v60, v62, vcc
	v_cndmask_b32_e32 v69, v61, v63, vcc
	s_nop 0
	v_mov_b32_dpp v68, v68 quad_perm:[1,0,3,2] row_mask:0xf bank_mask:0xf bound_ctrl:1
	v_mov_b32_dpp v69, v69 quad_perm:[1,0,3,2] row_mask:0xf bank_mask:0xf bound_ctrl:1
	v_cndmask_b32_e32 v60, v68, v60, vcc
	v_cndmask_b32_e32 v62, v62, v68, vcc
	v_cndmask_b32_e32 v61, v69, v61, vcc
	v_cndmask_b32_e32 v63, v63, v69, vcc
	v_cvt_pk_bf16_f32 v60, v60, v62
	v_add_lshl_u32 v62, v78, v117, 1
	global_store_dword v62, v60, s[0:1]
	v_cvt_pk_bf16_f32 v60, v61, v63
	v_add_lshl_u32 v61, v77, v117, 1
	global_store_dword v61, v60, s[0:1]
	v_cndmask_b32_e32 v60, v64, v66, vcc
	v_cndmask_b32_e32 v61, v65, v67, vcc
; DEVINL float sigm(float x) { return 1.f / (1.f + __expf(-x)); }
; template <int EPI, bool GATHER>
; DEVINL void gemm_tile(const Params& p, const u16* __restrict__ A, int lda, const int* __restrict__ rowidx,
;                       const u16* __restrict__ Bt, int ldb, int K, int brow, int bcol, int orow, int ocol) {
;     ...
; #pragma unroll
;   for (int ai = 0; ai < 2; ++ai)
; #pragma unroll
;     for (int m = 0; m < 4; ++m) {
;       const int rA = row0 + ai * HALF + m * 16 + (odd ? 2 : 0);
;       float gate[2] = {0.f, 0.f};
;       if (EPI == EPI_MOE2) { gate[0] = ((const float*)(ws + O_SELG))[rA]; gate[1] = ((const float*)(ws + O_SELG))[rA + 1]; }
; #pragma unroll
;       for (int bj = 0; bj < (EPI == EPI_HID ? 1 : 2); ++bj)
; #pragma unroll
;         for (int n = 0; n < 2; ++n) {
;           const int cc = bj * HALF + n * 16;
;           f32x4 v = acc[ai][bj][m][n];
;           if (EPI == EPI_HID) {
; #pragma unroll
;             for (int j = 0; j < 4; ++j) { const float a1 = acc[ai][0][m][n][j], a3 = acc[ai][1][m][n][j]; v[j] = a1 * sigm(a1) * a3; }
;           }
;           float lo[2], hi[2];
;           xchg_pairs(v, odd, lo, hi);
; #pragma unroll
;           for (int k = 0; k < 2; ++k) {
;             const unsigned row = (unsigned)(rA + k);
;             if (EPI == EPI_HID) {
;               *(unsigned*)(ws + O_HID + (row * 1024u + (unsigned)(colp + cc)) * 2u) = pk2(lo[k], hi[k]);
;             } else if (EPI == EPI_COLS) {
;               *(unsigned*)(ws + O_COLS + (row * (unsigned)NCP + (unsigned)(colp + cc)) * 2u) = pk2(lo[k], hi[k]);
	s_nop 0
	v_mov_b32_dpp v60, v60 quad_perm:[1,0,3,2] row_mask:0xf bank_mask:0xf bound_ctrl:1
	v_cndmask_b32_e32 v62, v60, v64, vcc
	v_cndmask_b32_e32 v60, v66, v60, vcc
	v_mov_b32_dpp v61, v61 quad_perm:[1,0,3,2] row_mask:0xf bank_mask:0xf bound_ctrl:1
	v_cvt_pk_bf16_f32 v60, v62, v60
	v_add_u32_e32 v62, 0x150000, v126
	v_cndmask_b32_e32 v63, v61, v65, vcc
	v_cndmask_b32_e32 v61, v67, v61, vcc
	v_add_lshl_u32 v64, v62, v129, 1
	global_store_dword v64, v60, s[0:1]
	v_cvt_pk_bf16_f32 v60, v63, v61
	v_add_u32_e32 v61, 0x152a00, v126
	v_add_lshl_u32 v63, v61, v129, 1
	global_store_dword v63, v60, s[0:1]
	v_cndmask_b32_e32 v60, v52, v54, vcc
	v_cndmask_b32_e32 v63, v53, v55, vcc
	s_nop 0
	v_mov_b32_dpp v60, v60 quad_perm:[1,0,3,2] row_mask:0xf bank_mask:0xf bound_ctrl:1
	v_mov_b32_dpp v63, v63 quad_perm:[1,0,3,2] row_mask:0xf bank_mask:0xf bound_ctrl:1
	v_cndmask_b32_e32 v52, v60, v52, vcc
	v_cndmask_b32_e32 v54, v54, v60, vcc
	v_cndmask_b32_e32 v53, v63, v53, vcc
	v_cndmask_b32_e32 v55, v55, v63, vcc
	v_cvt_pk_bf16_f32 v52, v52, v54
	v_add_lshl_u32 v54, v62, v124, 1
	global_store_dword v54, v52, s[0:1]
	v_cvt_pk_bf16_f32 v52, v53, v55
	v_add_lshl_u32 v53, v61, v124, 1
	global_store_dword v53, v52, s[0:1]
	v_cndmask_b32_e32 v52, v56, v58, vcc
	v_cndmask_b32_e32 v53, v57, v59, vcc
	s_nop 0
	v_mov_b32_dpp v52, v52 quad_perm:[1,0,3,2] row_mask:0xf bank_mask:0xf bound_ctrl:1
	v_mov_b32_dpp v53, v53 quad_perm:[1,0,3,2] row_mask:0xf bank_mask:0xf bound_ctrl:1
	v_cndmask_b32_e32 v54, v52, v56, vcc
	v_cndmask_b32_e32 v52, v58, v52, vcc
	v_cndmask_b32_e32 v55, v53, v57, vcc
	v_cndmask_b32_e32 v53, v59, v53, vcc
	v_cvt_pk_bf16_f32 v52, v54, v52
	v_add_lshl_u32 v54, v62, v116, 1
	global_store_dword v54, v52, s[0:1]
	v_cvt_pk_bf16_f32 v52, v55, v53
	v_add_lshl_u32 v53, v61, v116, 1
	global_store_dword v53, v52, s[0:1]
	v_cndmask_b32_e32 v52, v48, v50, vcc
	v_cndmask_b32_e32 v53, v49, v51, vcc
	s_nop 0
	v_mov_b32_dpp v52, v52 quad_perm:[1,0,3,2] row_mask:0xf bank_mask:0xf bound_ctrl:1
	v_mov_b32_dpp v53, v53 quad_perm:[1,0,3,2] row_mask:0xf bank_mask:0xf bound_ctrl:1
	v_cndmask_b32_e32 v48, v52, v48, vcc
	v_cndmask_b32_e32 v50, v50, v52, vcc
	v_cndmask_b32_e32 v49, v53, v49, vcc
	v_cndmask_b32_e32 v51, v51, v53, vcc
	v_cvt_pk_bf16_f32 v48, v48, v50
	v_add_lshl_u32 v50, v62, v117, 1
	global_store_dword v50, v48, s[0:1]
	v_cvt_pk_bf16_f32 v48, v49, v51
	v_add_lshl_u32 v49, v61, v117, 1
	global_store_dword v49, v48, s[0:1]
	v_cndmask_b32_e32 v48, v44, v46, vcc
	v_cndmask_b32_e32 v49, v45, v47, vcc
	s_nop 0
	v_mov_b32_dpp v48, v48 quad_perm:[1,0,3,2] row_mask:0xf bank_mask:0xf bound_ctrl:1
	v_cndmask_b32_e32 v44, v48, v44, vcc
	v_cndmask_b32_e32 v46, v46, v48, vcc
	v_mov_b32_dpp v49, v49 quad_perm:[1,0,3,2] row_mask:0xf bank_mask:0xf bound_ctrl:1
	v_cvt_pk_bf16_f32 v44, v44, v46
	v_add_u32_e32 v46, 0x17a000, v126
	v_cndmask_b32_e32 v45, v49, v45, vcc
	v_cndmask_b32_e32 v47, v47, v49, vcc
	v_add_lshl_u32 v48, v46, v129, 1
	global_store_dword v48, v44, s[0:1]
	v_cvt_pk_bf16_f32 v44, v45, v47
	v_add_u32_e32 v45, 0x17ca00, v126
	v_add_lshl_u32 v47, v45, v129, 1
	global_store_dword v47, v44, s[0:1]
	v_cndmask_b32_e32 v44, v36, v38, vcc
	v_cndmask_b32_e32 v47, v37, v39, vcc
	s_nop 0
	v_mov_b32_dpp v44, v44 quad_perm:[1,0,3,2] row_mask:0xf bank_mask:0xf bound_ctrl:1
	v_mov_b32_dpp v47, v47 quad_perm:[1,0,3,2] row_mask:0xf bank_mask:0xf bound_ctrl:1
	v_cndmask_b32_e32 v36, v44, v36, vcc
	v_cndmask_b32_e32 v38, v38, v44, vcc
	v_cndmask_b32_e32 v37, v47, v37, vcc
	v_cndmask_b32_e32 v39, v39, v47, vcc
	v_cvt_pk_bf16_f32 v36, v36, v38
	v_add_lshl_u32 v38, v46, v124, 1
	global_store_dword v38, v36, s[0:1]
	v_cvt_pk_bf16_f32 v36, v37, v39
	v_add_lshl_u32 v37, v45, v124, 1
	global_store_dword v37, v36, s[0:1]
	v_cndmask_b32_e32 v36, v40, v42, vcc
	v_cndmask_b32_e32 v37, v41, v43, vcc
	s_nop 0
	v_mov_b32_dpp v36, v36 quad_perm:[1,0,3,2] row_mask:0xf bank_mask:0xf bound_ctrl:1
	v_mov_b32_dpp v37, v37 quad_perm:[1,0,3,2] row_mask:0xf bank_mask:0xf bound_ctrl:1
	v_cndmask_b32_e32 v38, v36, v40, vcc
	v_cndmask_b32_e32 v36, v42, v36, vcc
	v_cndmask_b32_e32 v39, v37, v41, vcc
	v_cndmask_b32_e32 v37, v43, v37, vcc
	v_cvt_pk_bf16_f32 v36, v38, v36
	v_add_lshl_u32 v38, v46, v116, 1
	global_store_dword v38, v36, s[0:1]
	v_cvt_pk_bf16_f32 v36, v39, v37
	v_add_lshl_u32 v37, v45, v116, 1
	global_store_dword v37, v36, s[0:1]
	v_cndmask_b32_e32 v36, v32, v34, vcc
	v_cndmask_b32_e32 v37, v33, v35, vcc
	s_nop 0
	v_mov_b32_dpp v36, v36 quad_perm:[1,0,3,2] row_mask:0xf bank_mask:0xf bound_ctrl:1
	v_mov_b32_dpp v37, v37 quad_perm:[1,0,3,2] row_mask:0xf bank_mask:0xf bound_ctrl:1
	v_cndmask_b32_e32 v32, v36, v32, vcc
	v_cndmask_b32_e32 v34, v34, v36, vcc
	v_cndmask_b32_e32 v33, v37, v33, vcc
	v_cndmask_b32_e32 v35, v35, v37, vcc
	v_cvt_pk_bf16_f32 v32, v32, v34
	v_add_lshl_u32 v34, v46, v117, 1
	global_store_dword v34, v32, s[0:1]
	v_cvt_pk_bf16_f32 v32, v33, v35
	v_add_lshl_u32 v33, v45, v117, 1
	global_store_dword v33, v32, s[0:1]
	v_cndmask_b32_e32 v32, v28, v30, vcc
	v_cndmask_b32_e32 v33, v29, v31, vcc
; DEVINL float sigm(float x) { return 1.f / (1.f + __expf(-x)); }
; template <int EPI, bool GATHER>
; DEVINL void gemm_tile(const Params& p, const u16* __restrict__ A, int lda, const int* __restrict__ rowidx,
;                       const u16* __restrict__ Bt, int ldb, int K, int brow, int bcol, int orow, int ocol) {
;     ...
; #pragma unroll
;   for (int ai = 0; ai < 2; ++ai)
; #pragma unroll
;     for (int m = 0; m < 4; ++m) {
;       const int rA = row0 + ai * HALF + m * 16 + (odd ? 2 : 0);
;       float gate[2] = {0.f, 0.f};
;       if (EPI == EPI_MOE2) { gate[0] = ((const float*)(ws + O_SELG))[rA]; gate[1] = ((const float*)(ws + O_SELG))[rA + 1]; }
; #pragma unroll
;       for (int bj = 0; bj < (EPI == EPI_HID ? 1 : 2); ++bj)
; #pragma unroll
;         for (int n = 0; n < 2; ++n) {
;           const int cc = bj * HALF + n * 16;
;           f32x4 v = acc[ai][bj][m][n];
;           if (EPI == EPI_HID) {
; #pragma unroll
;             for (int j = 0; j < 4; ++j) { const float a1 = acc[ai][0][m][n][j], a3 = acc[ai][1][m][n][j]; v[j] = a1 * sigm(a1) * a3; }
;           }
;           float lo[2], hi[2];
;           xchg_pairs(v, odd, lo, hi);
; #pragma unroll
;           for (int k = 0; k < 2; ++k) {
;             const unsigned row = (unsigned)(rA + k);
;             if (EPI == EPI_HID) {
;               *(unsigned*)(ws + O_HID + (row * 1024u + (unsigned)(colp + cc)) * 2u) = pk2(lo[k], hi[k]);
;             } else if (EPI == EPI_COLS) {
;               *(unsigned*)(ws + O_COLS + (row * (unsigned)NCP + (unsigned)(colp + cc)) * 2u) = pk2(lo[k], hi[k]);
; DEVINL void phase1(const Params& p) {
;     ...
;   for (int t = blockIdx.x; t < ntiles; t += gridDim.x) {
;     int pm = t & 31, pn = t >> 5;
;     gemm_tile<EPI_COLS, false>(p, A, 2048, nullptr, Bt, 2048, 2048, pm * 256, pn * 256, pm * 256, pn * 256);
	s_nop 0
	v_mov_b32_dpp v32, v32 quad_perm:[1,0,3,2] row_mask:0xf bank_mask:0xf bound_ctrl:1
	v_cndmask_b32_e32 v28, v32, v28, vcc
	v_cndmask_b32_e32 v30, v30, v32, vcc
	v_mov_b32_dpp v33, v33 quad_perm:[1,0,3,2] row_mask:0xf bank_mask:0xf bound_ctrl:1
	v_cvt_pk_bf16_f32 v28, v28, v30
	v_add_u32_e32 v30, 0x1a4000, v126
	v_cndmask_b32_e32 v29, v33, v29, vcc
	v_cndmask_b32_e32 v31, v31, v33, vcc
	v_add_lshl_u32 v32, v30, v129, 1
	global_store_dword v32, v28, s[0:1]
	v_cvt_pk_bf16_f32 v28, v29, v31
	v_add_u32_e32 v29, 0x1a6a00, v126
	v_add_lshl_u32 v31, v29, v129, 1
	global_store_dword v31, v28, s[0:1]
	v_cndmask_b32_e32 v28, v20, v22, vcc
	v_cndmask_b32_e32 v31, v21, v23, vcc
	s_nop 0
	v_mov_b32_dpp v28, v28 quad_perm:[1,0,3,2] row_mask:0xf bank_mask:0xf bound_ctrl:1
	v_mov_b32_dpp v31, v31 quad_perm:[1,0,3,2] row_mask:0xf bank_mask:0xf bound_ctrl:1
	v_cndmask_b32_e32 v20, v28, v20, vcc
	v_cndmask_b32_e32 v22, v22, v28, vcc
	v_cndmask_b32_e32 v21, v31, v21, vcc
	v_cndmask_b32_e32 v23, v23, v31, vcc
	v_cvt_pk_bf16_f32 v20, v20, v22
	v_add_lshl_u32 v22, v30, v124, 1
	global_store_dword v22, v20, s[0:1]
	v_cvt_pk_bf16_f32 v20, v21, v23
	v_add_lshl_u32 v21, v29, v124, 1
	global_store_dword v21, v20, s[0:1]
	v_cndmask_b32_e32 v20, v24, v26, vcc
	v_cndmask_b32_e32 v21, v25, v27, vcc
	s_nop 0
	v_mov_b32_dpp v20, v20 quad_perm:[1,0,3,2] row_mask:0xf bank_mask:0xf bound_ctrl:1
	v_mov_b32_dpp v21, v21 quad_perm:[1,0,3,2] row_mask:0xf bank_mask:0xf bound_ctrl:1
	v_cndmask_b32_e32 v22, v20, v24, vcc
	v_cndmask_b32_e32 v20, v26, v20, vcc
	v_cndmask_b32_e32 v23, v21, v25, vcc
	v_cndmask_b32_e32 v21, v27, v21, vcc
	v_cvt_pk_bf16_f32 v20, v22, v20
	v_add_lshl_u32 v22, v30, v116, 1
	global_store_dword v22, v20, s[0:1]
	v_cvt_pk_bf16_f32 v20, v23, v21
	v_add_lshl_u32 v21, v29, v116, 1
	global_store_dword v21, v20, s[0:1]
	v_cndmask_b32_e32 v20, v16, v18, vcc
	v_cndmask_b32_e32 v21, v17, v19, vcc
	s_nop 0
	v_mov_b32_dpp v20, v20 quad_perm:[1,0,3,2] row_mask:0xf bank_mask:0xf bound_ctrl:1
	v_mov_b32_dpp v21, v21 quad_perm:[1,0,3,2] row_mask:0xf bank_mask:0xf bound_ctrl:1
	v_cndmask_b32_e32 v16, v20, v16, vcc
	v_cndmask_b32_e32 v18, v18, v20, vcc
	v_cndmask_b32_e32 v17, v21, v17, vcc
	v_cndmask_b32_e32 v19, v19, v21, vcc
	v_cvt_pk_bf16_f32 v16, v16, v18
	v_add_lshl_u32 v18, v30, v117, 1
	global_store_dword v18, v16, s[0:1]
	v_cvt_pk_bf16_f32 v16, v17, v19
	v_add_lshl_u32 v17, v29, v117, 1
	global_store_dword v17, v16, s[0:1]
	v_cndmask_b32_e32 v16, v12, v14, vcc
	v_cndmask_b32_e32 v17, v13, v15, vcc
	s_nop 0
	v_mov_b32_dpp v16, v16 quad_perm:[1,0,3,2] row_mask:0xf bank_mask:0xf bound_ctrl:1
	v_cndmask_b32_e32 v12, v16, v12, vcc
	v_cndmask_b32_e32 v14, v14, v16, vcc
	v_mov_b32_dpp v17, v17 quad_perm:[1,0,3,2] row_mask:0xf bank_mask:0xf bound_ctrl:1
	v_cvt_pk_bf16_f32 v12, v12, v14
	v_add_u32_e32 v14, 0x1ce000, v126
	v_cndmask_b32_e32 v13, v17, v13, vcc
	v_cndmask_b32_e32 v15, v15, v17, vcc
	v_add_lshl_u32 v16, v14, v129, 1
	global_store_dword v16, v12, s[0:1]
	v_cvt_pk_bf16_f32 v12, v13, v15
	v_add_u32_e32 v13, 0x1d0a00, v126
	v_add_lshl_u32 v15, v13, v129, 1
	global_store_dword v15, v12, s[0:1]
	v_cndmask_b32_e32 v12, v4, v6, vcc
	v_cndmask_b32_e32 v15, v5, v7, vcc
	s_nop 0
	v_mov_b32_dpp v12, v12 quad_perm:[1,0,3,2] row_mask:0xf bank_mask:0xf bound_ctrl:1
	v_mov_b32_dpp v15, v15 quad_perm:[1,0,3,2] row_mask:0xf bank_mask:0xf bound_ctrl:1
	v_cndmask_b32_e32 v4, v12, v4, vcc
	v_cndmask_b32_e32 v6, v6, v12, vcc
	v_cndmask_b32_e32 v5, v15, v5, vcc
	v_cndmask_b32_e32 v7, v7, v15, vcc
	v_cvt_pk_bf16_f32 v4, v4, v6
	v_add_lshl_u32 v6, v14, v124, 1
	global_store_dword v6, v4, s[0:1]
	v_cvt_pk_bf16_f32 v4, v5, v7
	v_add_lshl_u32 v5, v13, v124, 1
	global_store_dword v5, v4, s[0:1]
	v_cndmask_b32_e32 v4, v8, v10, vcc
	v_cndmask_b32_e32 v5, v9, v11, vcc
	s_nop 0
	v_mov_b32_dpp v4, v4 quad_perm:[1,0,3,2] row_mask:0xf bank_mask:0xf bound_ctrl:1
	v_mov_b32_dpp v5, v5 quad_perm:[1,0,3,2] row_mask:0xf bank_mask:0xf bound_ctrl:1
	v_cndmask_b32_e32 v6, v4, v8, vcc
	v_cndmask_b32_e32 v4, v10, v4, vcc
	v_cndmask_b32_e32 v7, v5, v9, vcc
	v_cndmask_b32_e32 v5, v11, v5, vcc
	v_cvt_pk_bf16_f32 v4, v6, v4
	v_add_lshl_u32 v6, v14, v116, 1
	global_store_dword v6, v4, s[0:1]
	v_cvt_pk_bf16_f32 v4, v7, v5
	v_add_lshl_u32 v5, v13, v116, 1
	global_store_dword v5, v4, s[0:1]
	v_cndmask_b32_e32 v4, v0, v2, vcc
	v_cndmask_b32_e32 v5, v1, v3, vcc
	s_nop 0
	v_mov_b32_dpp v4, v4 quad_perm:[1,0,3,2] row_mask:0xf bank_mask:0xf bound_ctrl:1
	v_mov_b32_dpp v5, v5 quad_perm:[1,0,3,2] row_mask:0xf bank_mask:0xf bound_ctrl:1
	v_cndmask_b32_e32 v0, v4, v0, vcc
	v_cndmask_b32_e32 v2, v2, v4, vcc
	v_cndmask_b32_e32 v1, v5, v1, vcc
	v_cndmask_b32_e32 v3, v3, v5, vcc
	v_cvt_pk_bf16_f32 v0, v0, v2
	v_add_lshl_u32 v2, v14, v117, 1
	global_store_dword v2, v0, s[0:1]
	v_cvt_pk_bf16_f32 v0, v1, v3
	v_add_lshl_u32 v1, v13, v117, 1
	global_store_dword v1, v0, s[0:1]
	s_add_i32 s47, s47, s94
	s_add_i32 s3, s3, s40
	s_add_i32 s41, s41, s42
	s_cmpk_lt_i32 s47, 0x500
	s_nop 0
	s_barrier
	s_cbranch_scc0 .LBB0_230
